# v109 plus removal of 94 dead address-arithmetic instructions in the sliding-window staging section
# speedup vs baseline: 1.0068x; 1.0068x over previous
; __device__ __forceinline__ int ptid_(int wave) { int l_; asm volatile("v_mbcnt_lo_u32_b32 %0, -1, 0\n\tv_mbcnt_hi_u32_b32 %0, -1, %0" : "=v"(l_)); return (wave << 6) | l_; }
; __device__ void swa_item(const Params& p, int item) {
;   float* misc = (float*)(p.ws + MISC_OFF);
;   bfu* buf = (bfu*)(p.ws + R_OFF);
;   const int pat = item >> 10; const int rem = item & 1023;
;   const int b = rem >> 7, head = (rem >> 5) & 3, sub = rem & 31;
;   const int dil = (pat == 0) ? 1 : (pat == 1 ? 4 : 16);
;   const int nqb = 32 / dil;
;   const int r = sub / nqb, qb = sub % nqb;
;   int tid = ptid_(p.tid); asm volatile("" : "+v"(tid)); const int w = tid >> 6, lane = tid & 63, c = lane & 15, q = lane >> 4;
;   bfu* Vt = (bfu*)smem;
;   bfu* Ks = Vt + 128 * 280;
;   bfu* Pl = Ks + w * (16 * 168);
;   const long rowb = (long)b * TSEQ;
;   const int qcol = pat * 512 + head * 128, kcol = 1536 + qcol, vcol = 3072 + qcol;
;   __syncthreads();
;   _Pragma("unroll") for (int i = 0; i < 4; ++i) {
;     int co = tid + 512 * i; int c8 = co & 15, kp = co >> 4;
;     int j0 = qb * 128 - 128 + 2 * kp;
;     const int j0c = (j0 >= 0) ? j0 : 0;
;     bf16x8 v0 = *(const bf16x8*)(buf + (rowb + (long)j0c * dil + r) * 4608 + vcol + c8 * 8);
;     bf16x8 v1 = *(const bf16x8*)(buf + (rowb + (long)(j0c + 1) * dil + r) * 4608 + vcol + c8 * 8);
;     if (j0 < 0) { v0 = (bf16x8){0, 0, 0, 0, 0, 0, 0, 0}; v1 = v0; }
;     const int chs = ((kp >> 2) ^ c8) * 8 + ((2 * kp) & 7);
;     _Pragma("unroll") for (int e = 0; e < 8; ++e)
;       *(unsigned*)(Vt + (c8 * 8 + e) * 280 + chs) = (unsigned)(bfu)v0[e] | ((unsigned)(bfu)v1[e] << 16);
;   }
;   _Pragma("unroll") for (int i = 0; i < 8; ++i) {
;     int co = tid + 512 * i; int c8 = co & 15, kj = co >> 4;
;     int j = qb * 128 - 128 + kj; j = (j >= 0) ? j : 0;
;     *(bf16x8*)(Ks + kj * 136 + c8 * 8) = *(const bf16x8*)(buf + (rowb + (long)j * dil + r) * 4608 + kcol + c8 * 8);
;   }
;   for (int i = tid; i < 128 * 12; i += NTHR) { int dv = i / 12, k2 = i % 12; *(unsigned*)(Vt + dv * 280 + 256 + 2 * k2) = 0u; }
;   bf16x8 qf[4];
;   { long qrow = rowb + (long)(qb * 128 + w * 16 + c) * dil + r;
;     _Pragma("unroll") for (int kk = 0; kk < 4; ++kk) qf[kk] = *(const bf16x8*)(buf + qrow * 4608 + qcol + kk * 32 + q * 8); }
.LBB0_102:
	s_cmpk_gt_i32 s21, 0xbff
	s_cbranch_scc1 .LBB0_113
	s_ashr_i32 s88, s21, 10
	s_bfe_u32 s23, s21, 0x20005
	s_and_b32 s0, s21, 31
	s_cmp_eq_u32 s88, 1
	s_cselect_b32 s1, 2, 4
	s_cmpk_gt_u32 s21, 0x3ff
	s_cselect_b32 s22, s1, 0
	s_lshr_b32 s1, 32, s22
	s_sub_i32 s2, 5, s22
	s_add_i32 s1, s1, -1
	s_lshr_b32 s2, s0, s2
	s_and_b32 s34, s1, s0
	s_lshl_b32 s0, s21, 5
	s_and_b32 s1, s0, 0x7000
	s_lshl_b32 s0, s88, 9
	s_lshl_b32 s3, s23, 7
	s_or_b32 s0, s3, s0
	v_readlane_b32 s18, v254, 13
	s_lshl_b32 s35, s34, 7
	s_or_b32 s18, s2, s1
	s_ashr_i32 s1, s0, 31
	v_mbcnt_lo_u32_b32 v0, -1, 0
	v_mbcnt_hi_u32_b32 v0, -1, v0
	s_add_i32 s12, s35, 0xffffff80
	v_or_b32_e32 v50, s33, v0
	s_lshl_b64 s[2:3], s[0:1], 1
	s_add_u32 s52, s16, s2
	v_and_b32_e32 v55, 15, v50
	s_addc_u32 s53, s17, s3
	v_lshlrev_b32_e32 v0, 4, v55
	v_ashrrev_i32_e32 v13, 3, v50
	s_waitcnt lgkmcnt(0)
	v_lshl_add_u64 v[2:3], s[52:53], 0, v[0:1]
	v_and_b32_e32 v0, -2, v13
	v_add_u32_e32 v14, s12, v0
	s_mov_b64 s[2:3], 0x1800
	v_max_i32_e32 v0, 0, v14
	v_lshl_add_u64 v[10:11], v[2:3], 0, s[2:3]
	v_lshlrev_b64 v[2:3], s22, v[0:1]
	v_or_b32_e32 v0, 1, v0
	v_readlane_b32 s19, v254, 14
	v_lshlrev_b64 v[6:7], s22, v[0:1]
	s_nop 0
	v_lshl_add_u64 v[2:3], v[2:3], 0, s[18:19]
	v_lshl_add_u64 v[6:7], v[6:7], 0, s[18:19]
	v_mad_u64_u32 v[4:5], s[2:3], v2, s89, v[10:11]
	v_mad_u64_u32 v[8:9], s[2:3], v6, s89, v[10:11]
	v_mad_u32_u24 v5, v3, s89, v5
	v_mad_u32_u24 v9, v7, s89, v9
	s_barrier
	v_lshlrev_b32_e32 v140, 4, v55
	v_mov_b32_e32 v141, 0
	v_lshl_add_u64 v[140:141], s[52:53], 0, v[140:141]
	s_mov_b64 s[2:3], 0x1800
	v_lshl_add_u64 v[142:143], v[140:141], 0, s[2:3]
	v_lshrrev_b32_e32 v144, 4, v50
	v_lshl_add_u32 v145, v144, 1, s12
	v_max_i32_e32 v146, 0, v145
	v_lshlrev_b32_e32 v147, s22, v146
	v_add_u32_e32 v147, s18, v147
	v_mad_u64_u32 v[148:149], vcc, v147, s89, v[142:143]
	global_load_dwordx4 v[76:79], v[148:149], off
	v_or_b32_e32 v146, 1, v146
	v_lshlrev_b32_e32 v147, s22, v146
	v_add_u32_e32 v147, s18, v147
	v_mad_u64_u32 v[148:149], vcc, v147, s89, v[142:143]
	global_load_dwordx4 v[80:83], v[148:149], off
	v_add_u32_e32 v146, 64, v145
	v_max_i32_e32 v146, 0, v146
	v_lshlrev_b32_e32 v147, s22, v146
	v_add_u32_e32 v147, s18, v147
	v_mad_u64_u32 v[148:149], vcc, v147, s89, v[142:143]
	global_load_dwordx4 v[84:87], v[148:149], off
	v_or_b32_e32 v146, 1, v146
	v_lshlrev_b32_e32 v147, s22, v146
	v_add_u32_e32 v147, s18, v147
	v_mad_u64_u32 v[148:149], vcc, v147, s89, v[142:143]
	global_load_dwordx4 v[88:91], v[148:149], off
	v_add_u32_e32 v146, 128, v145
	v_max_i32_e32 v146, 0, v146
	v_lshlrev_b32_e32 v147, s22, v146
	v_add_u32_e32 v147, s18, v147
	v_mad_u64_u32 v[148:149], vcc, v147, s89, v[142:143]
	global_load_dwordx4 v[92:95], v[148:149], off
	v_or_b32_e32 v146, 1, v146
	v_lshlrev_b32_e32 v147, s22, v146
	v_add_u32_e32 v147, s18, v147
	v_mad_u64_u32 v[148:149], vcc, v147, s89, v[142:143]
	global_load_dwordx4 v[96:99], v[148:149], off
	v_add_u32_e32 v146, 192, v145
	v_max_i32_e32 v146, 0, v146
	v_lshlrev_b32_e32 v147, s22, v146
	v_add_u32_e32 v147, s18, v147
	v_mad_u64_u32 v[148:149], vcc, v147, s89, v[142:143]
	global_load_dwordx4 v[100:103], v[148:149], off
	v_or_b32_e32 v146, 1, v146
	v_lshlrev_b32_e32 v147, s22, v146
	v_add_u32_e32 v147, s18, v147
	v_mad_u64_u32 v[148:149], vcc, v147, s89, v[142:143]
	global_load_dwordx4 v[104:107], v[148:149], off
	v_add_u32_e32 v145, s12, v144
	v_max_i32_e32 v146, 0, v145
	v_lshlrev_b32_e32 v147, s22, v146
	v_add_u32_e32 v147, s18, v147
	v_mad_u64_u32 v[148:149], vcc, v147, s89, v[140:141]
	global_load_dwordx4 v[108:111], v[148:149], off offset:3072
	v_add_u32_e32 v146, 32, v145
	v_max_i32_e32 v146, 0, v146
	v_lshlrev_b32_e32 v147, s22, v146
	v_add_u32_e32 v147, s18, v147
	v_mad_u64_u32 v[148:149], vcc, v147, s89, v[140:141]
	global_load_dwordx4 v[112:115], v[148:149], off offset:3072
	v_add_u32_e32 v146, 64, v145
	v_max_i32_e32 v146, 0, v146
	v_lshlrev_b32_e32 v147, s22, v146
	v_add_u32_e32 v147, s18, v147
	v_mad_u64_u32 v[148:149], vcc, v147, s89, v[140:141]
	global_load_dwordx4 v[116:119], v[148:149], off offset:3072
	v_add_u32_e32 v146, 96, v145
	v_max_i32_e32 v146, 0, v146
	v_lshlrev_b32_e32 v147, s22, v146
	v_add_u32_e32 v147, s18, v147
	v_mad_u64_u32 v[148:149], vcc, v147, s89, v[140:141]
	global_load_dwordx4 v[120:123], v[148:149], off offset:3072
	v_add_u32_e32 v146, 128, v145
	v_max_i32_e32 v146, 0, v146
	v_lshlrev_b32_e32 v147, s22, v146
	v_add_u32_e32 v147, s18, v147
	v_mad_u64_u32 v[148:149], vcc, v147, s89, v[140:141]
	global_load_dwordx4 v[124:127], v[148:149], off offset:3072
	v_add_u32_e32 v146, 160, v145
	v_max_i32_e32 v146, 0, v146
	v_lshlrev_b32_e32 v147, s22, v146
	v_add_u32_e32 v147, s18, v147
	v_mad_u64_u32 v[148:149], vcc, v147, s89, v[140:141]
	global_load_dwordx4 v[128:131], v[148:149], off offset:3072
	v_add_u32_e32 v146, 192, v145
	v_max_i32_e32 v146, 0, v146
	v_lshlrev_b32_e32 v147, s22, v146
	v_add_u32_e32 v147, s18, v147
	v_mad_u64_u32 v[148:149], vcc, v147, s89, v[140:141]
	global_load_dwordx4 v[132:135], v[148:149], off offset:3072
	v_add_u32_e32 v146, 224, v145
	v_max_i32_e32 v146, 0, v146
	v_lshlrev_b32_e32 v147, s22, v146
	v_add_u32_e32 v147, s18, v147
	v_mad_u64_u32 v[148:149], vcc, v147, s89, v[140:141]
	global_load_dwordx4 v[136:139], v[148:149], off offset:3072
	v_mov_b32_e32 v243, s18
	v_lshrrev_b32_e32 v243, 12, v243
	v_add_u32_e32 v243, 2, v243
	v_lshrrev_b32_e32 v243, 3, v243
	v_sub_u32_e32 v243, 1, v243
	v_lshlrev_b32_e32 v243, 13, v243
	v_add_u32_e32 v243, s18, v243
	v_lshrrev_b32_e32 v244, 1, v50
	v_and_b32_e32 v245, 1, v50
	v_add_u32_e32 v246, s12, v244
	v_max_i32_e32 v246, 0, v246
	v_lshlrev_b32_e32 v246, s22, v246
	v_add_u32_e32 v246, v243, v246
	v_mul_u32_u24_e32 v246, 0x2400, v246
	v_lshl_add_u32 v246, v245, 7, v246
	v_add_u32_e32 v240, 0xc00, v246
	v_add_u32_e32 v241, 0x1800, v246
	v_and_b32_e32 v244, 0x7f, v244
	v_add_u32_e32 v244, s35, v244
	v_lshlrev_b32_e32 v244, s22, v244
	v_add_u32_e32 v244, v243, v244
	v_mul_u32_u24_e32 v244, 0x2400, v244
	v_lshl_add_u32 v242, v245, 7, v244
	s_waitcnt vmcnt(14)
; __device__ void swa_item(const Params& p, int item) {
;     ...
;   _Pragma("unroll") for (int i = 0; i < 4; ++i) {
;     int co = tid + 512 * i; int c8 = co & 15, kp = co >> 4;
;     int j0 = qb * 128 - 128 + 2 * kp;
;     const int j0c = (j0 >= 0) ? j0 : 0;
;     bf16x8 v0 = *(const bf16x8*)(buf + (rowb + (long)j0c * dil + r) * 4608 + vcol + c8 * 8);
;     bf16x8 v1 = *(const bf16x8*)(buf + (rowb + (long)(j0c + 1) * dil + r) * 4608 + vcol + c8 * 8);
;     if (j0 < 0) { v0 = (bf16x8){0, 0, 0, 0, 0, 0, 0, 0}; v1 = v0; }
;     const int chs = ((kp >> 2) ^ c8) * 8 + ((2 * kp) & 7);
;     _Pragma("unroll") for (int e = 0; e < 8; ++e)
;       *(unsigned*)(Vt + (c8 * 8 + e) * 280 + chs) = (unsigned)(bfu)v0[e] | ((unsigned)(bfu)v1[e] << 16);
;   }
;   _Pragma("unroll") for (int i = 0; i < 8; ++i) {
;     int co = tid + 512 * i; int c8 = co & 15, kj = co >> 4;
;     int j = qb * 128 - 128 + kj; j = (j >= 0) ? j : 0;
;     *(bf16x8*)(Ks + kj * 136 + c8 * 8) = *(const bf16x8*)(buf + (rowb + (long)j * dil + r) * 4608 + kcol + c8 * 8);
;   }
;   for (int i = tid; i < 128 * 12; i += NTHR) { int dv = i / 12, k2 = i % 12; *(unsigned*)(Vt + dv * 280 + 256 + 2 * k2) = 0u; }
	v_mov_b64_e32 v[2:3], v[76:77]
	v_mov_b64_e32 v[4:5], v[78:79]
	v_ashrrev_i32_e32 v12, 6, v50
	v_mov_b64_e32 v[6:7], v[80:81]
	v_mov_b64_e32 v[8:9], v[82:83]
	v_cmp_gt_i32_e32 vcc, 0, v14
	v_lshlrev_b32_e32 v13, 1, v13
	v_and_b32_e32 v14, 12, v13
	s_mov_b32 s13, 0x1000504
	v_mul_u32_u24_e32 v13, 0x1180, v55
	s_mov_b32 s14, 0x3020706
	v_add_u32_e32 v51, 0x200, v50
	v_cndmask_b32_e64 v2, v2, 0, vcc
	v_cndmask_b32_e64 v3, v3, 0, vcc
	v_cndmask_b32_e64 v0, v9, 0, vcc
	v_bitop3_b32 v9, v12, v50, 15 bitop3:0x78
	v_cndmask_b32_e64 v6, v6, 0, vcc
	v_lshl_add_u32 v9, v9, 4, 0
	v_cndmask_b32_e64 v7, v7, 0, vcc
	v_perm_b32 v15, v2, v6, s13
	v_add3_u32 v9, v9, v14, v13
	v_perm_b32 v2, v2, v6, s14
	v_cndmask_b32_e64 v8, v8, 0, vcc
	v_cndmask_b32_e64 v4, v4, 0, vcc
	ds_write2_b32 v9, v15, v2 offset1:140
	v_perm_b32 v2, v3, v7, s13
	v_perm_b32 v3, v3, v7, s14
	v_add_u32_e32 v6, 0x400, v9
	v_cndmask_b32_e64 v5, v5, 0, vcc
	ds_write2_b32 v6, v2, v3 offset0:24 offset1:164
	v_perm_b32 v2, v4, v8, s13
	v_perm_b32 v3, v4, v8, s14
	v_add_u32_e32 v4, 0x800, v9
	ds_write2_b32 v4, v2, v3 offset0:48 offset1:188
	v_perm_b32 v2, v5, v0, s13
	v_perm_b32 v0, v5, v0, s14
	v_add_u32_e32 v3, 0xc00, v9
	v_ashrrev_i32_e32 v14, 3, v51
	ds_write2_b32 v3, v2, v0 offset0:72 offset1:212
	v_and_b32_e32 v0, -2, v14
	v_add_u32_e32 v15, s12, v0
	s_waitcnt vmcnt(12)
	v_mov_b64_e32 v[2:3], v[84:85]
	v_mov_b64_e32 v[4:5], v[86:87]
	v_cmp_gt_i32_e32 vcc, 0, v15
	v_mov_b64_e32 v[6:7], v[88:89]
	v_mov_b64_e32 v[8:9], v[90:91]
	v_lshlrev_b32_e32 v14, 1, v14
	v_and_b32_e32 v14, 12, v14
	v_cndmask_b32_e64 v2, v2, 0, vcc
	v_cndmask_b32_e64 v3, v3, 0, vcc
	v_cndmask_b32_e64 v0, v9, 0, vcc
	v_ashrrev_i32_e32 v9, 6, v51
	v_bitop3_b32 v9, v9, v50, 15 bitop3:0x78
	v_cndmask_b32_e64 v6, v6, 0, vcc
	v_lshl_add_u32 v9, v9, 4, 0
	v_cndmask_b32_e64 v7, v7, 0, vcc
	v_perm_b32 v15, v2, v6, s13
	v_add3_u32 v9, v9, v14, v13
	v_perm_b32 v2, v2, v6, s14
	v_cndmask_b32_e64 v8, v8, 0, vcc
	v_cndmask_b32_e64 v4, v4, 0, vcc
	ds_write2_b32 v9, v15, v2 offset1:140
	v_perm_b32 v2, v3, v7, s13
	v_perm_b32 v3, v3, v7, s14
	v_add_u32_e32 v6, 0x400, v9
	v_cndmask_b32_e64 v5, v5, 0, vcc
	ds_write2_b32 v6, v2, v3 offset0:24 offset1:164
	v_perm_b32 v2, v4, v8, s13
	v_perm_b32 v3, v4, v8, s14
	v_add_u32_e32 v4, 0x800, v9
	v_add_u32_e32 v14, 0x400, v50
	ds_write2_b32 v4, v2, v3 offset0:48 offset1:188
	v_perm_b32 v2, v5, v0, s13
	v_perm_b32 v0, v5, v0, s14
	v_add_u32_e32 v3, 0xc00, v9
	v_ashrrev_i32_e32 v15, 3, v14
	ds_write2_b32 v3, v2, v0 offset0:72 offset1:212
	v_and_b32_e32 v0, -2, v15
	v_add_u32_e32 v16, s12, v0
	s_waitcnt vmcnt(10)
	v_mov_b64_e32 v[2:3], v[92:93]
	v_mov_b64_e32 v[4:5], v[94:95]
	v_cmp_gt_i32_e32 vcc, 0, v16
	v_mov_b64_e32 v[6:7], v[96:97]
	v_mov_b64_e32 v[8:9], v[98:99]
	v_lshlrev_b32_e32 v15, 1, v15
	v_and_b32_e32 v15, 12, v15
	v_cndmask_b32_e64 v2, v2, 0, vcc
	v_cndmask_b32_e64 v3, v3, 0, vcc
	v_cndmask_b32_e64 v0, v9, 0, vcc
	v_ashrrev_i32_e32 v9, 6, v14
	v_bitop3_b32 v9, v9, v50, 15 bitop3:0x78
	v_cndmask_b32_e64 v6, v6, 0, vcc
	v_lshl_add_u32 v9, v9, 4, 0
	v_cndmask_b32_e64 v7, v7, 0, vcc
	v_perm_b32 v16, v2, v6, s13
	v_add3_u32 v9, v9, v15, v13
	v_perm_b32 v2, v2, v6, s14
	v_cndmask_b32_e64 v8, v8, 0, vcc
	v_cndmask_b32_e64 v4, v4, 0, vcc
	ds_write2_b32 v9, v16, v2 offset1:140
	v_perm_b32 v2, v3, v7, s13
	v_perm_b32 v3, v3, v7, s14
	v_add_u32_e32 v6, 0x400, v9
	v_cndmask_b32_e64 v5, v5, 0, vcc
	ds_write2_b32 v6, v2, v3 offset0:24 offset1:164
	v_perm_b32 v2, v4, v8, s13
	v_perm_b32 v3, v4, v8, s14
	v_add_u32_e32 v4, 0x800, v9
	v_add_u32_e32 v15, 0x600, v50
	ds_write2_b32 v4, v2, v3 offset0:48 offset1:188
	v_perm_b32 v2, v5, v0, s13
	v_perm_b32 v0, v5, v0, s14
	v_add_u32_e32 v3, 0xc00, v9
	v_ashrrev_i32_e32 v16, 3, v15
	ds_write2_b32 v3, v2, v0 offset0:72 offset1:212
	v_and_b32_e32 v0, -2, v16
	v_add_u32_e32 v17, s12, v0
	s_waitcnt vmcnt(8)
	v_mov_b64_e32 v[2:3], v[100:101]
	v_mov_b64_e32 v[4:5], v[102:103]
	v_cmp_gt_i32_e32 vcc, 0, v17
	v_mov_b64_e32 v[6:7], v[104:105]
	v_mov_b64_e32 v[8:9], v[106:107]
	v_lshlrev_b32_e32 v10, 1, v16
	v_and_b32_e32 v10, 12, v10
	v_readlane_b32 s2, v254, 10
	v_cndmask_b32_e64 v2, v2, 0, vcc
	v_cndmask_b32_e64 v3, v3, 0, vcc
	v_cndmask_b32_e64 v0, v9, 0, vcc
	v_ashrrev_i32_e32 v9, 6, v15
	v_bitop3_b32 v9, v9, v50, 15 bitop3:0x78
	v_cndmask_b32_e64 v6, v6, 0, vcc
	v_lshl_add_u32 v9, v9, 4, 0
	v_cndmask_b32_e64 v7, v7, 0, vcc
	v_perm_b32 v11, v2, v6, s13
	v_add3_u32 v9, v9, v10, v13
	v_perm_b32 v2, v2, v6, s14
	v_cndmask_b32_e64 v8, v8, 0, vcc
	v_cndmask_b32_e64 v4, v4, 0, vcc
	ds_write2_b32 v9, v11, v2 offset1:140
	v_perm_b32 v2, v3, v7, s13
	v_perm_b32 v3, v3, v7, s14
	v_add_u32_e32 v6, 0x400, v9
	v_cndmask_b32_e64 v5, v5, 0, vcc
	ds_write2_b32 v6, v2, v3 offset0:24 offset1:164
	v_perm_b32 v2, v4, v8, s13
	v_perm_b32 v3, v4, v8, s14
	v_add_u32_e32 v4, 0x800, v9
	ds_write2_b32 v4, v2, v3 offset0:48 offset1:188
	v_perm_b32 v2, v5, v0, s13
	v_perm_b32 v0, v5, v0, s14
	v_add_u32_e32 v3, 0xc00, v9
	v_ashrrev_i32_e32 v7, 4, v50
	ds_write2_b32 v3, v2, v0 offset0:72 offset1:212
	v_lshlrev_b32_e32 v0, 3, v50
	v_and_b32_e32 v0, 0x78, v0
	v_lshlrev_b32_e32 v0, 1, v0
	v_mov_b64_e32 v[8:9], s[52:53]
	v_add_u32_e32 v6, s2, v0
	s_waitcnt vmcnt(7)
	v_mov_b64_e32 v[2:3], v[108:109]
	v_mov_b64_e32 v[4:5], v[110:111]
	s_movk_i32 s13, 0x110
	v_mad_u64_u32 v[10:11], s[2:3], v7, s13, v[6:7]
	v_ashrrev_i32_e32 v7, 4, v51
	ds_write_b128 v10, v[2:5]
	s_waitcnt vmcnt(6)
	v_mov_b64_e32 v[2:3], v[112:113]
	v_mov_b64_e32 v[4:5], v[114:115]
	v_mad_u64_u32 v[10:11], s[2:3], v7, s13, v[6:7]
	v_ashrrev_i32_e32 v7, 4, v14
	ds_write_b128 v10, v[2:5]
	s_waitcnt vmcnt(5)
	v_mov_b64_e32 v[2:3], v[116:117]
	v_mov_b64_e32 v[4:5], v[118:119]
	v_mad_u64_u32 v[10:11], s[2:3], v7, s13, v[6:7]
	v_ashrrev_i32_e32 v7, 4, v15
	ds_write_b128 v10, v[2:5]
	s_waitcnt vmcnt(4)
	v_mov_b64_e32 v[2:3], v[120:121]
	v_mov_b64_e32 v[4:5], v[122:123]
	v_mad_u64_u32 v[10:11], s[2:3], v7, s13, v[6:7]
	ds_write_b128 v10, v[2:5]
	v_add_u32_e32 v2, 0x800, v50
	v_ashrrev_i32_e32 v7, 4, v2
	s_waitcnt vmcnt(3)
	v_mov_b64_e32 v[2:3], v[124:125]
	v_mov_b64_e32 v[4:5], v[126:127]
	v_mad_u64_u32 v[10:11], s[2:3], v7, s13, v[6:7]
	ds_write_b128 v10, v[2:5]
	v_add_u32_e32 v2, 0xa00, v50
	v_ashrrev_i32_e32 v7, 4, v2
	s_waitcnt vmcnt(2)
	v_mov_b64_e32 v[2:3], v[128:129]
	v_mov_b64_e32 v[4:5], v[130:131]
	v_mad_u64_u32 v[10:11], s[2:3], v7, s13, v[6:7]
	ds_write_b128 v10, v[2:5]
	v_add_u32_e32 v2, 0xc00, v50
	v_ashrrev_i32_e32 v7, 4, v2
	s_waitcnt vmcnt(1)
	v_mov_b64_e32 v[2:3], v[132:133]
	v_mov_b64_e32 v[4:5], v[134:135]
	v_mad_u64_u32 v[10:11], s[2:3], v7, s13, v[6:7]
	v_writelane_b32 v254, s18, 13
	ds_write_b128 v10, v[2:5]
	v_add_u32_e32 v2, 0xe00, v50
	v_ashrrev_i32_e32 v7, 4, v2
	s_waitcnt vmcnt(0)
	v_mov_b64_e32 v[2:3], v[136:137]
	v_mov_b64_e32 v[4:5], v[138:139]
	v_mad_u64_u32 v[6:7], s[2:3], v7, s13, v[6:7]
	s_movk_i32 s2, 0x600
	v_writelane_b32 v254, s19, 14
	v_cmp_gt_i32_e32 vcc, s2, v50
	ds_write_b128 v6, v[2:5]
	s_and_saveexec_b64 s[12:13], vcc
	s_cbranch_execz .LBB0_111
; __device__ void swa_item(const Params& p, int item) {
;     ...
;   for (int i = tid; i < 128 * 12; i += NTHR) { int dv = i / 12, k2 = i % 12; *(unsigned*)(Vt + dv * 280 + 256 + 2 * k2) = 0u; }
	v_max_i32_e32 v2, 0x400, v50
	v_sub_u32_e32 v2, v2, v50
	v_add_u32_e32 v3, 0x1ff, v2
	v_cmp_lt_u32_e32 vcc, s24, v3
	s_mov_b64 s[18:19], -1
	v_mov_b32_e32 v2, v50
	s_and_saveexec_b64 s[14:15], vcc
	s_cbranch_execz .LBB0_108
	v_lshrrev_b32_e32 v2, 9, v3
	v_add_u32_e32 v4, 1, v2
	v_and_b32_e32 v5, 0xfffffe, v4
	s_mov_b64 s[18:19], 0
	v_mov_b32_e32 v6, v5
	v_mov_b64_e32 v[2:3], v[50:51]
	s_mov_b32 s2, 0x2aaaaaab
	s_movk_i32 s3, 0x230
